# mixer cache-copy loop also throttled (s_sleep 64 per item) on top of the deferred-conversion throttle
# baseline (speedup 1.0000x reference)
; __device__ __forceinline__ int tid_() { int t = threadIdx.x; asm volatile("" : "+v"(t)); return t; }
; __device__ __forceinline__ float bf2f(u16 h) { return __uint_as_float(((unsigned)h) << 16); }
; __device__ void copy_item(const P& p, int item) {
;   int e = item * 2048 + tid_();
; #pragma unroll
;   for (int k = 0; k < 8; ++k, e += 256) {
;     int i = e;
;     if (i < 131072) {
;       int which = i >> 16; i &= 65535;
;       int d = i & 63, kvh = (i >> 6) & 1, wpos = (i >> 7) & 127, b = i >> 14;
;       float v = bf2f(p_proj[((size_t)b * 8192 + 8064 + wpos) * INW + 512 + which * 128 + kvh * 64 + d]);
;       p.out[(which ? O_VP : O_KP) + i] = v;
;     } else if ((i -= 131072) < 18432) {
;       int c = i % 1536, j = (i / 1536) % 3, b = i / 4608;
;       p.out[O_CP + i] = bf2f(p_proj[((size_t)b * 8192 + 8189 + j) * INW + 768 + c]);
;     } else if ((i -= 18432) < 4194304) {
;       int which = i >> 21; i &= 2097151;
;       int d = i & 63, kvh = (i >> 6) & 1, wpos = (i >> 7) & 127, b = i >> 14;
;       float v;
;       if (wpos < 120) v = (which ? p.cv : p.ck)[(((size_t)b * 128 + wpos + 8) * 2 + kvh) * 64 + d];
;       else v = bf2f(p_proj[((size_t)TP + b * 8 + wpos - 120) * INW + 512 + which * 128 + kvh * 64 + d]);
;       p.out[(which ? O_VS : O_KS) + i] = v;
;     } else {
;       i -= 4194304;
;       int c = i % 1536, j = (i / 1536) % 3, b = i / 4608;
;       p.out[O_CS + i] = bf2f(p_proj[((size_t)TP + b * 8 + 5 + j) * INW + 768 + c]);
;     }
;   }
; }
.LBB0_349:
	s_sleep 64
	v_mov_b32_e32 v15, v220
	s_add_i32 s4, s14, s13
	s_nop 0
	v_add_u32_e32 v16, s4, v15
	v_add_u32_e32 v2, 0xffff0000, v16
	v_and_b32_e32 v4, 63, v15
	v_cmp_lt_i32_e32 vcc, s16, v2
	s_and_saveexec_b64 s[4:5], vcc
	s_xor_b64 s[4:5], exec, s[4:5]
	s_cbranch_execz .LBB0_363
	v_cmp_lt_u32_e32 vcc, s17, v2
	s_and_saveexec_b64 s[6:7], vcc
	s_xor_b64 s[6:7], exec, s[6:7]
	s_cbranch_execz .LBB0_360
	v_cmp_lt_u32_e32 vcc, s18, v2
	s_and_saveexec_b64 s[8:9], vcc
	s_xor_b64 s[8:9], exec, s[8:9]
	s_cbranch_execz .LBB0_353
	v_add_u32_e32 v3, 0xffbcb800, v16
	v_mul_hi_u32 v0, v3, s19
	v_lshrrev_b32_e32 v5, 10, v0
	v_mul_u32_u24_e32 v0, 0x600, v5
	v_mul_hi_u32 v6, v5, s20
	v_sub_u32_e32 v0, v3, v0
	v_mul_u32_u24_e32 v6, 3, v6
	v_mul_hi_u32 v3, v3, s21
	v_sub_u32_e32 v5, v5, v6
	v_lshrrev_b32_e32 v3, 7, v3
	v_and_or_b32 v3, v3, s22, v5
	v_add_u32_e32 v3, 0x8005, v3
	v_mov_b64_e32 v[6:7], s[0:1]
	v_mad_u64_u32 v[6:7], s[10:11], v3, s23, v[6:7]
	v_lshl_add_u64 v[6:7], v[0:1], 1, v[6:7]
	global_load_ushort v0, v[6:7], off
	v_readlane_b32 s44, v228, 2
	v_mov_b32_e32 v3, v1
	v_readlane_b32 s48, v228, 6
	v_readlane_b32 s49, v228, 7
	v_readlane_b32 s45, v228, 3
	v_readlane_b32 s46, v228, 4
	v_lshl_add_u64 v[6:7], v[2:3], 2, s[48:49]
	v_add_co_u32_e32 v6, vcc, 0x8480000, v6
	v_readlane_b32 s47, v228, 5
	s_nop 0
	v_addc_co_u32_e32 v7, vcc, 0, v7, vcc
	v_readlane_b32 s50, v228, 8
	v_readlane_b32 s51, v228, 9
	s_waitcnt vmcnt(0)
	v_lshlrev_b32_e32 v0, 16, v0
	global_store_dword v[6:7], v0, off
